# phase skew, graded: the four groups of a batch class start the merged GEMM 0/3.4/6.8/10 us apart
# baseline (speedup 1.0000x reference)
; __global__ void __launch_bounds__(NTHREADS, 2) skel_fwd(Args args) {
;     ...
;     if (IN(4)) {
;     ...
;         { pg8::SchedP3m S{F.G, (int)blockIdx.x, (const char*)F.SBQ, (const char*)F.Wbr_t};
;           pg8::EpiMergedR E{F.G0, F.G2, F.MRG};
;           pg8::gemm_phase<pg8::EpiMergedR, pg8::SchedP3m, true, true, 3>(F.lds, DH, S, E); }
.LBB0_561:
	s_bfe_u32 s2, s90, 0x20003
.Lskew_loop:
	s_cmp_eq_u32 s2, 0
	s_cbranch_scc1 .Lskew_skip
	s_sleep 127
	s_sub_u32 s2, s2, 1
	s_branch .Lskew_loop
